# v15 + safety pad after the register-parking LDS store in the NSA window-loop preheader
# speedup vs baseline: 1.1603x; 1.0005x over previous
;     ...
;   if (kt >= kt_end) { hook(); return; }
;   const bf16x8 ones = bf16x8{0x3F80, 0x3F80, 0x3F80, 0x3F80, 0x3F80, 0x3F80, 0x3F80, 0x3F80};
;   f32x4 L[NQ * NMAP];
; #pragma unroll
;   for (int i = 0; i < NQ * NMAP; ++i) L[i] = f32x4{0.f, 0.f, 0.f, 0.f};
;   int nxt = next_tile(kt);
;   {
;     u32x4 fk[TK][2], fv[TK][2];
; #pragma unroll
;     for (int t = 0; t < TK; ++t)
; #pragma unroll
;       for (int i = 0; i < 2; ++i) {
;         fk[t][i] = *(const u32x4*)(gk + (size_t)((kt + t) * 64 + i * 32) * kstride);
;         fv[t][i] = *(const u32x4*)(gv + (size_t)(i * 32) * vtstride + (kt + t) * 64);
;       }
;     if (nxt < kt_end) gload(nxt);
;     hook();
;     __syncthreads();
; #pragma unroll
;     for (int t = 0; t < TK; ++t)
; #pragma unroll
;       for (int i = 0; i < 2; ++i) {
;         *(u32x4*)(wk + t * TSZ + i * 32 * 64) = fk[t][i];
;         *(u32x4*)(wv + t * TSZ + i * 32 * 72) = fv[t][i];
;       }
;   }
;   __syncthreads();
; __device__ void item_nsa(const Params& p, int layer, int b, int g, int qt, unsigned char* smem) {
;     ...
;     __syncthreads();
;     selq[0] = sSel[l15]; selq[1] = sSel[16 + l15];
;     tilemask = sSel[32];
.LBB0_161:
	s_or_b64 exec, exec, s[0:1]
	v_lshlrev_b32_e32 v122, 2, v120
	v_lshrrev_b32_e32 v3, 4, v121
	v_or_b32_e32 v123, 0x12000, v122
	v_or_b32_e32 v122, 0x12040, v122
	v_xor_b32_e32 v119, v3, v121
	s_waitcnt lgkmcnt(0)
	s_barrier
	ds_read_b32 v207, v123
	ds_read_b32 v208, v122
	ds_read_b32 v122, v212
	v_lshlrev_b32_e32 v117, 7, v118
	v_lshlrev_b32_e32 v119, 4, v119
	s_movk_i32 s0, 0x70
	v_lshlrev_b32_e32 v118, 4, v118
	v_and_b32_e32 v2, 15, v121
	v_bfe_u32 v116, v121, 4, 2
	v_and_or_b32 v209, v119, s0, v117
	v_add3_u32 v230, v117, v118, v0
	s_mov_b64 s[0:1], 0x20000
	v_bfe_u32 v0, v121, 1, 3
	v_lshl_add_u64 v[198:199], v[196:197], 0, s[0:1]
	v_lshlrev_b32_e32 v231, 2, v116
	v_lshlrev_b32_e32 v232, 7, v2
	v_mul_u32_u24_e32 v233, 0x90, v2
	v_bitop3_b32 v2, v3, v0, 3 bitop3:0x6c
	v_bitop3_b32 v0, v116, v0, 4 bitop3:0x36
	s_lshl_b32 s0, s29, 5
	v_lshlrev_b32_e32 v234, 4, v2
	v_lshlrev_b32_e32 v235, 4, v0
	v_or_b32_e32 v0, s0, v231
	v_mov_b32_e32 v2, v1
	v_mov_b32_e32 v3, v1
	s_waitcnt lgkmcnt(0)
	v_readfirstlane_b32 s46, v122
	s_barrier
	s_waitcnt vmcnt(7)
	ds_write_b128 v209, v[88:91]
	s_waitcnt vmcnt(5)
	ds_write_b128 v230, v[96:99] offset:9216
	ds_write_b128 v209, v[84:87] offset:4096
	s_waitcnt vmcnt(1)
	ds_write_b128 v230, v[112:115] offset:13824
	ds_write_b128 v209, v[104:107] offset:18432
	ds_write_b128 v230, v[92:95] offset:27648
	ds_write_b128 v209, v[100:103] offset:22528
	s_waitcnt vmcnt(0)
	ds_write_b128 v230, v[108:111] offset:32256
	s_add_i32 s1, s0, s86
	v_sub_u32_e32 v236, v120, v231
	v_sub_u32_e32 v237, v0, v120
	v_mov_b32_e32 v0, v1
	v_mov_b64_e32 v[86:87], v[2:3]
	v_mov_b64_e32 v[90:91], v[2:3]
	v_mov_b64_e32 v[98:99], v[2:3]
	v_mov_b64_e32 v[102:103], v[2:3]
	v_mov_b64_e32 v[106:107], v[2:3]
	v_mov_b64_e32 v[118:119], v[2:3]
	v_mov_b64_e32 v[122:123], v[2:3]
	v_mov_b64_e32 v[114:115], v[2:3]
	v_mov_b64_e32 v[110:111], v[2:3]
	v_mov_b64_e32 v[94:95], v[2:3]
	s_add_i32 s40, s86, 0x7f
	s_sub_i32 s41, 0x7ff, s1
	s_mov_b32 s42, 0
	v_mov_b64_e32 v[84:85], v[0:1]
	v_mov_b64_e32 v[88:89], v[0:1]
	v_mov_b64_e32 v[96:97], v[0:1]
	v_mov_b64_e32 v[100:101], v[0:1]
	v_mov_b64_e32 v[104:105], v[0:1]
	v_mov_b64_e32 v[116:117], v[0:1]
	v_mov_b64_e32 v[120:121], v[0:1]
	v_mov_b64_e32 v[112:113], v[0:1]
	v_mov_b64_e32 v[108:109], v[0:1]
	v_mov_b64_e32 v[92:93], v[0:1]
	s_movk_i32 s75, 0x210
	s_mov_b32 s77, 0x40000
	s_mov_b32 s78, 0x60000
	s_waitcnt lgkmcnt(0)
	s_barrier
	v_lshlrev_b32_e32 v0, 4, v210
	v_add_u32_e32 v0, 0x12110, v0
	ds_write_b128 v0, v[48:51]
	s_nop 1
	v_mul_f32_e32 v49, 0x40b17218, v188
	v_mul_f32_e32 v50, 2.0, v49
	v_mul_f32_e32 v51, 0x40400000, v49
	v_mov_b32_e32 v48, 0
